# POOLMIX residual stage: the old-residual loads of rows m=1..3 issued together with each column group's m=0 batch (was 12 serialized load->vmcnt(0) round trips per unit)
# baseline (speedup 1.0000x reference)
.LBB0_549:
	s_or_b64 exec, exec, s[26:27]
	v_add_u32_e32 v0, 0, v241
	v_add_u32_e32 v14, 0x20400, v0
	s_waitcnt lgkmcnt(0)
	s_barrier
	ds_read_b128 v[2:5], v14
	ds_read_b128 v[6:9], v14 offset:16
	v_or_b32_e32 v104, s63, v209
	v_ashrrev_i32_e32 v105, 31, v104
	v_mov_b32_e32 v106, 0
	s_waitcnt lgkmcnt(1)
	v_mov_b32_e32 v10, v3
	v_mov_b32_e32 v11, v4
	v_mov_b32_e32 v3, v5
	v_pk_add_f32 v[2:3], v[10:11], v[2:3]
	s_waitcnt lgkmcnt(0)
	v_mov_b32_e32 v4, v8
	v_mov_b32_e32 v5, v6
	v_mov_b32_e32 v6, v9
	v_pk_add_f32 v[4:5], v[4:5], v[6:7]
	v_add_f32_e32 v0, v2, v3
	v_add_f32_e32 v0, v0, v5
	v_add_f32_e32 v0, v4, v0
	v_fmamk_f32 v0, v0, 0x3a800000, v229
	v_cmp_gt_f32_e32 vcc, s5, v0
	v_mul_f32_e32 v2, 0x4f800000, v0
	s_nop 0
	v_cndmask_b32_e32 v0, v0, v2, vcc
	v_sqrt_f32_e32 v2, v0
	s_nop 0
	v_add_u32_e32 v3, -1, v2
	v_fma_f32 v4, -v3, v2, v0
	v_cmp_ge_f32_e64 s[42:43], 0, v4
	v_add_u32_e32 v4, 1, v2
	s_nop 0
	v_cndmask_b32_e64 v3, v2, v3, s[42:43]
	v_fma_f32 v2, -v4, v2, v0
	v_cmp_lt_f32_e64 s[42:43], 0, v2
	s_nop 1
	v_cndmask_b32_e64 v2, v3, v4, s[42:43]
	v_mul_f32_e32 v3, 0x37800000, v2
	v_cndmask_b32_e32 v2, v2, v3, vcc
	v_cmp_class_f32_e32 vcc, v0, v230
	s_nop 1
	v_cndmask_b32_e32 v0, v2, v0, vcc
	v_div_scale_f32 v2, s[16:17], v0, v0, 1.0
	v_rcp_f32_e32 v3, v2
	s_nop 0
	v_fma_f32 v4, -v2, v3, 1.0
	v_fmac_f32_e32 v3, v4, v3
	v_div_scale_f32 v4, vcc, 1.0, v0, 1.0
	v_mul_f32_e32 v5, v4, v3
	v_fma_f32 v6, -v2, v5, v4
	v_fmac_f32_e32 v5, v6, v3
	v_fma_f32 v2, -v2, v5, v4
	v_div_fmas_f32 v2, v2, v3, v5
	v_div_fixup_f32 v54, v2, v0, 1.0
	ds_read_b128 v[2:5], v14 offset:512
	ds_read_b128 v[6:9], v14 offset:528
	v_pk_mul_f32 v[68:69], v[176:177], v[54:55] op_sel_hi:[1,0]
	v_pk_mul_f32 v[112:113], v[174:175], v[54:55] op_sel_hi:[1,0]
	v_pk_mul_f32 v[114:115], v[172:173], v[54:55] op_sel_hi:[1,0]
	s_waitcnt lgkmcnt(1)
	v_add_f32_e32 v0, v2, v3
	v_add_f32_e32 v2, v4, v5
	v_add_f32_e32 v0, v0, v2
	s_waitcnt lgkmcnt(0)
	v_add_f32_e32 v2, v6, v7
	v_add_f32_e32 v0, v0, v2
	v_add_f32_e32 v2, v8, v9
	v_add_f32_e32 v0, v2, v0
	v_fmamk_f32 v0, v0, 0x3a800000, v229
	v_cmp_gt_f32_e32 vcc, s5, v0
	v_mul_f32_e32 v2, 0x4f800000, v0
	v_pk_mul_f32 v[116:117], v[170:171], v[54:55] op_sel_hi:[1,0]
	v_cndmask_b32_e32 v0, v0, v2, vcc
	v_sqrt_f32_e32 v2, v0
	s_nop 0
	v_add_u32_e32 v3, -1, v2
	v_fma_f32 v4, -v3, v2, v0
	v_cmp_ge_f32_e64 s[42:43], 0, v4
	v_add_u32_e32 v4, 1, v2
	s_nop 0
	v_cndmask_b32_e64 v3, v2, v3, s[42:43]
	v_fma_f32 v2, -v4, v2, v0
	v_cmp_lt_f32_e64 s[42:43], 0, v2
	s_nop 1
	v_cndmask_b32_e64 v2, v3, v4, s[42:43]
	v_mul_f32_e32 v3, 0x37800000, v2
	v_cndmask_b32_e32 v2, v2, v3, vcc
	v_cmp_class_f32_e32 vcc, v0, v230
	s_nop 1
	v_cndmask_b32_e32 v0, v2, v0, vcc
	v_div_scale_f32 v2, s[16:17], v0, v0, 1.0
	v_rcp_f32_e32 v3, v2
	s_nop 0
	v_fma_f32 v4, -v2, v3, 1.0
	v_fmac_f32_e32 v3, v4, v3
	v_div_scale_f32 v4, vcc, 1.0, v0, 1.0
	v_mul_f32_e32 v5, v4, v3
	v_fma_f32 v6, -v2, v5, v4
	v_fmac_f32_e32 v5, v6, v3
	v_fma_f32 v2, -v2, v5, v4
	v_div_fmas_f32 v2, v2, v3, v5
	v_div_fixup_f32 v0, v2, v0, 1.0
	v_lshlrev_b64 v[2:3], 10, v[104:105]
	v_lshl_add_u64 v[2:3], v[2:3], 0, v[212:213]
	v_lshlrev_b64 v[66:67], 1, v[2:3]
	v_lshl_add_u64 v[64:65], s[36:37], 0, v[66:67]
	ds_read_b128 v[26:29], v14 offset:1024
	ds_read_b128 v[22:25], v14 offset:1040
	ds_read_b128 v[10:13], v14 offset:1536
	ds_read_b128 v[6:9], v14 offset:1552
	global_load_dwordx4 v[14:17], v[218:219], off offset:16
	global_load_dwordx4 v[18:21], v[218:219], off
	global_load_dwordx4 v[2:5], v[64:65], off
	s_cmp_lg_u32 s68, 4
	s_cbranch_scc1 .Lpmh_skip0
	s_mov_b64 s[52:53], 0x8000
	s_mov_b64 s[54:55], 0x10000
	s_mov_b64 s[56:57], 0x18000
	v_lshl_add_u64 v[204:205], v[64:65], 0, s[52:53]
	global_load_dwordx4 v[192:195], v[204:205], off
	v_lshl_add_u64 v[204:205], v[64:65], 0, s[54:55]
	global_load_dwordx4 v[196:199], v[204:205], off
	v_lshl_add_u64 v[204:205], v[64:65], 0, s[56:57]
	global_load_dwordx4 v[200:203], v[204:205], off
.Lpmh_skip0:
	s_and_b64 vcc, exec, s[40:41]
	v_mov_b32_e32 v105, 0
	s_waitcnt vmcnt(2)
	v_pk_mul_f32 v[114:115], v[14:15], v[114:115]
	s_waitcnt vmcnt(1)
	v_pk_mul_f32 v[68:69], v[18:19], v[68:69]
	s_waitcnt vmcnt(0)
	v_lshlrev_b32_e32 v55, 16, v2
	v_and_b32_e32 v2, 0xffff0000, v2
	v_add_f32_e32 v55, v68, v55
	v_add_f32_e32 v2, v69, v2
	v_pk_mul_f32 v[112:113], v[20:21], v[112:113]
	v_cvt_pk_bf16_f32 v2, v55, v2
	v_lshlrev_b32_e32 v55, 16, v3
	v_and_b32_e32 v3, 0xffff0000, v3
	v_add_f32_e32 v55, v112, v55
	v_add_f32_e32 v3, v113, v3
	v_cvt_pk_bf16_f32 v3, v55, v3
	v_lshlrev_b32_e32 v55, 16, v4
	v_and_b32_e32 v4, 0xffff0000, v4
	v_add_f32_e32 v55, v114, v55
	v_add_f32_e32 v4, v115, v4
	v_pk_mul_f32 v[116:117], v[16:17], v[116:117]
	v_cvt_pk_bf16_f32 v4, v55, v4
	v_lshlrev_b32_e32 v55, 16, v5
	v_and_b32_e32 v5, 0xffff0000, v5
	v_lshl_add_u64 v[68:69], s[44:45], 0, v[66:67]
	v_or_b32_e32 v66, 16, v104
	v_add_f32_e32 v5, v117, v5
	v_ashrrev_i32_e32 v67, 31, v66
	v_add_f32_e32 v55, v116, v55
	v_cvt_pk_bf16_f32 v5, v55, v5
	global_store_dwordx4 v[68:69], v[2:5], off
	s_cbranch_vccnz .LBB0_551
	v_lshlrev_b64 v[112:113], 10, v[66:67]
	v_lshl_add_u64 v[112:113], v[112:113], 0, v[212:213]
	v_lshlrev_b64 v[116:117], 1, v[112:113]
	v_lshl_add_u64 v[112:113], s[36:37], 0, v[116:117]
	v_mov_b64_e32 v[112:113], v[192:193]
	v_mov_b64_e32 v[114:115], v[194:195]
	v_pk_mul_f32 v[120:121], v[188:189], v[0:1] op_sel_hi:[1,0]
	v_pk_mul_f32 v[118:119], v[186:187], v[0:1] op_sel_hi:[1,0]
	v_pk_mul_f32 v[120:121], v[18:19], v[120:121]
	v_pk_mul_f32 v[118:119], v[20:21], v[118:119]
	v_pk_mul_f32 v[124:125], v[184:185], v[0:1] op_sel_hi:[1,0]
	v_pk_mul_f32 v[122:123], v[182:183], v[0:1] op_sel_hi:[1,0]
	v_pk_mul_f32 v[124:125], v[14:15], v[124:125]
	v_pk_mul_f32 v[122:123], v[16:17], v[122:123]
	v_lshl_add_u64 v[116:117], s[44:45], 0, v[116:117]
	v_lshlrev_b32_e32 v55, 16, v112
	v_and_b32_e32 v105, 0xffff0000, v112
	v_add_f32_e32 v55, v120, v55
	v_add_f32_e32 v105, v121, v105
	v_cvt_pk_bf16_f32 v112, v55, v105
	v_lshlrev_b32_e32 v55, 16, v113
	v_and_b32_e32 v105, 0xffff0000, v113
	v_add_f32_e32 v55, v118, v55
	v_add_f32_e32 v105, v119, v105
	v_cvt_pk_bf16_f32 v113, v55, v105
	v_lshlrev_b32_e32 v55, 16, v114
	v_and_b32_e32 v105, 0xffff0000, v114
	v_add_f32_e32 v55, v124, v55
	v_add_f32_e32 v105, v125, v105
	v_cvt_pk_bf16_f32 v114, v55, v105
	v_lshlrev_b32_e32 v55, 16, v115
	v_and_b32_e32 v105, 0xffff0000, v115
	v_add_f32_e32 v55, v122, v55
	v_add_f32_e32 v105, v123, v105
	v_cvt_pk_bf16_f32 v115, v55, v105
	global_store_dwordx4 v[116:117], v[112:115], off
	v_lshlrev_b32_e32 v117, 16, v113
	v_lshlrev_b32_e32 v116, 16, v112
	v_and_b32_e32 v113, 0xffff0000, v113
	v_and_b32_e32 v112, 0xffff0000, v112
	v_pk_mul_f32 v[112:113], v[112:113], v[112:113]
	v_and_b32_e32 v119, 0xffff0000, v114
	v_and_b32_e32 v118, 0xffff0000, v115
	v_pk_fma_f32 v[112:113], v[116:117], v[116:117], v[112:113]
	v_lshlrev_b32_e32 v116, 16, v115
	v_lshlrev_b32_e32 v117, 16, v114
	v_pk_mul_f32 v[114:115], v[118:119], v[118:119]
	v_add_f32_e32 v55, v112, v113
	v_pk_fma_f32 v[114:115], v[116:117], v[116:117], v[114:115]
	s_nop 0
	v_add_f32_e32 v55, v115, v55
	v_add_f32_e32 v105, v114, v55
.LBB0_551:
	s_waitcnt lgkmcnt(3)
	v_add_f32_e32 v26, v26, v27
	v_add_f32_e32 v27, v28, v29
	v_add_f32_e32 v26, v26, v27
	s_waitcnt lgkmcnt(2)
	v_add_f32_e32 v22, v22, v23
	v_add_f32_e32 v22, v26, v22
	v_add_f32_e32 v23, v24, v25
	v_add_f32_e32 v22, v23, v22
	v_fmamk_f32 v22, v22, 0x3a800000, v229
	v_mul_f32_e32 v23, 0x4f800000, v22
	v_cmp_gt_f32_e32 vcc, s5, v22
	v_or_b32_e32 v28, 32, v104
	v_ashrrev_i32_e32 v29, 31, v28
	v_cndmask_b32_e32 v22, v22, v23, vcc
	v_sqrt_f32_e32 v23, v22
	s_nop 0
	v_add_u32_e32 v24, -1, v23
	v_fma_f32 v25, -v24, v23, v22
	v_cmp_ge_f32_e64 s[42:43], 0, v25
	v_add_u32_e32 v25, 1, v23
	s_nop 0
	v_cndmask_b32_e64 v24, v23, v24, s[42:43]
	v_fma_f32 v23, -v25, v23, v22
	v_cmp_lt_f32_e64 s[42:43], 0, v23
	s_nop 1
	v_cndmask_b32_e64 v23, v24, v25, s[42:43]
	v_mul_f32_e32 v24, 0x37800000, v23
	v_cndmask_b32_e32 v23, v23, v24, vcc
	v_cmp_class_f32_e32 vcc, v22, v230
	s_nop 1
	v_cndmask_b32_e32 v22, v23, v22, vcc
	v_div_scale_f32 v23, s[16:17], v22, v22, 1.0
	v_rcp_f32_e32 v24, v23
	s_nop 0
	v_fma_f32 v25, -v23, v24, 1.0
	v_fmac_f32_e32 v24, v25, v24
	v_div_scale_f32 v25, vcc, 1.0, v22, 1.0
	v_mul_f32_e32 v26, v25, v24
	v_fma_f32 v27, -v23, v26, v25
	v_fmac_f32_e32 v26, v27, v24
	v_fma_f32 v23, -v23, v26, v25
	v_div_fmas_f32 v23, v23, v24, v26
	v_div_fixup_f32 v26, v23, v22, 1.0
	s_and_b64 vcc, exec, s[40:41]
	s_cbranch_vccnz .LBB0_553
	v_lshlrev_b64 v[22:23], 10, v[28:29]
	v_lshl_add_u64 v[22:23], v[22:23], 0, v[212:213]
	v_lshlrev_b64 v[106:107], 1, v[22:23]
	v_lshl_add_u64 v[22:23], s[36:37], 0, v[106:107]
	v_mov_b64_e32 v[22:23], v[196:197]
	v_mov_b64_e32 v[24:25], v[198:199]
	v_pk_mul_f32 v[114:115], v[180:181], v[26:27] op_sel_hi:[1,0]
	v_pk_mul_f32 v[112:113], v[178:179], v[26:27] op_sel_hi:[1,0]
	v_pk_mul_f32 v[114:115], v[18:19], v[114:115]
	v_pk_mul_f32 v[70:71], v[70:71], v[26:27] op_sel_hi:[1,0]
	v_pk_mul_f32 v[88:89], v[88:89], v[26:27] op_sel_hi:[1,0]
	v_pk_mul_f32 v[112:113], v[20:21], v[112:113]
	v_pk_mul_f32 v[88:89], v[14:15], v[88:89]
	v_pk_mul_f32 v[70:71], v[16:17], v[70:71]
	v_lshlrev_b32_e32 v27, 16, v22
	v_and_b32_e32 v22, 0xffff0000, v22
	v_add_f32_e32 v27, v114, v27
	v_add_f32_e32 v22, v115, v22
	v_cvt_pk_bf16_f32 v22, v27, v22
	v_lshlrev_b32_e32 v27, 16, v23
	v_and_b32_e32 v23, 0xffff0000, v23
	v_add_f32_e32 v27, v112, v27
	v_add_f32_e32 v23, v113, v23
	v_cvt_pk_bf16_f32 v23, v27, v23
	v_lshlrev_b32_e32 v27, 16, v24
	v_and_b32_e32 v24, 0xffff0000, v24
	v_add_f32_e32 v27, v88, v27
	v_add_f32_e32 v24, v89, v24
	v_cvt_pk_bf16_f32 v24, v27, v24
	v_lshlrev_b32_e32 v27, 16, v25
	v_and_b32_e32 v25, 0xffff0000, v25
	v_add_f32_e32 v27, v70, v27
	v_add_f32_e32 v25, v71, v25
	v_lshl_add_u64 v[70:71], s[44:45], 0, v[106:107]
	v_cvt_pk_bf16_f32 v25, v27, v25
	global_store_dwordx4 v[70:71], v[22:25], off
	v_lshlrev_b32_e32 v71, 16, v23
	v_lshlrev_b32_e32 v70, 16, v22
	v_and_b32_e32 v23, 0xffff0000, v23
	v_and_b32_e32 v22, 0xffff0000, v22
	v_pk_mul_f32 v[22:23], v[22:23], v[22:23]
	v_and_b32_e32 v89, 0xffff0000, v24
	v_and_b32_e32 v88, 0xffff0000, v25
	v_pk_fma_f32 v[22:23], v[70:71], v[70:71], v[22:23]
	v_lshlrev_b32_e32 v70, 16, v25
	v_lshlrev_b32_e32 v71, 16, v24
	v_pk_mul_f32 v[24:25], v[88:89], v[88:89]
	v_add_f32_e32 v22, v22, v23
	v_pk_fma_f32 v[24:25], v[70:71], v[70:71], v[24:25]
	s_nop 0
	v_add_f32_e32 v22, v25, v22
	v_add_f32_e32 v106, v24, v22
.LBB0_553:
	s_waitcnt lgkmcnt(1)
	v_add_f32_e32 v10, v10, v11
	v_add_f32_e32 v11, v12, v13
	v_add_f32_e32 v10, v10, v11
	s_waitcnt lgkmcnt(0)
	v_add_f32_e32 v6, v6, v7
	v_add_f32_e32 v6, v10, v6
	v_add_f32_e32 v7, v8, v9
	v_add_f32_e32 v6, v7, v6
	v_fmamk_f32 v6, v6, 0x3a800000, v229
	v_mul_f32_e32 v7, 0x4f800000, v6
	v_cmp_gt_f32_e32 vcc, s5, v6
	v_or_b32_e32 v88, 48, v104
	v_mov_b32_e32 v27, 0
	v_cndmask_b32_e32 v6, v6, v7, vcc
	v_sqrt_f32_e32 v7, v6
	v_ashrrev_i32_e32 v89, 31, v88
	v_add_u32_e32 v8, -1, v7
	v_fma_f32 v9, -v8, v7, v6
	v_cmp_ge_f32_e64 s[42:43], 0, v9
	v_add_u32_e32 v9, 1, v7
	s_nop 0
	v_cndmask_b32_e64 v8, v7, v8, s[42:43]
	v_fma_f32 v7, -v9, v7, v6
	v_cmp_lt_f32_e64 s[42:43], 0, v7
	s_nop 1
	v_cndmask_b32_e64 v7, v8, v9, s[42:43]
	v_mul_f32_e32 v8, 0x37800000, v7
	v_cndmask_b32_e32 v7, v7, v8, vcc
	v_cmp_class_f32_e32 vcc, v6, v230
	s_nop 1
	v_cndmask_b32_e32 v6, v7, v6, vcc
	v_div_scale_f32 v7, s[16:17], v6, v6, 1.0
	v_rcp_f32_e32 v8, v7
	s_nop 0
	v_fma_f32 v9, -v7, v8, 1.0
	v_fmac_f32_e32 v8, v9, v8
	v_div_scale_f32 v9, vcc, 1.0, v6, 1.0
	v_mul_f32_e32 v10, v9, v8
	v_fma_f32 v11, -v7, v10, v9
	v_fmac_f32_e32 v10, v11, v8
	v_fma_f32 v7, -v7, v10, v9
	v_div_fmas_f32 v7, v7, v8, v10
	v_div_fixup_f32 v70, v7, v6, 1.0
	s_and_b64 vcc, exec, s[40:41]
	s_cbranch_vccnz .LBB0_555
	v_lshlrev_b64 v[6:7], 10, v[88:89]
	v_lshl_add_u64 v[6:7], v[6:7], 0, v[212:213]
	v_lshlrev_b64 v[10:11], 1, v[6:7]
	v_lshl_add_u64 v[6:7], s[36:37], 0, v[10:11]
	v_mov_b64_e32 v[6:7], v[200:201]
	v_mov_b64_e32 v[8:9], v[202:203]
	v_pk_mul_f32 v[12:13], v[110:111], v[70:71] op_sel_hi:[1,0]
	v_pk_mul_f32 v[22:23], v[108:109], v[70:71] op_sel_hi:[1,0]
	v_pk_mul_f32 v[24:25], v[102:103], v[70:71] op_sel_hi:[1,0]
	v_pk_mul_f32 v[100:101], v[100:101], v[70:71] op_sel_hi:[1,0]
	v_pk_mul_f32 v[12:13], v[20:21], v[12:13]
	v_pk_mul_f32 v[18:19], v[18:19], v[22:23]
	v_pk_mul_f32 v[16:17], v[16:17], v[24:25]
	v_pk_mul_f32 v[14:15], v[14:15], v[100:101]
	v_lshl_add_u64 v[10:11], s[44:45], 0, v[10:11]
	v_lshlrev_b32_e32 v20, 16, v6
	v_and_b32_e32 v6, 0xffff0000, v6
	v_lshlrev_b32_e32 v21, 16, v7
	v_and_b32_e32 v7, 0xffff0000, v7
	v_lshlrev_b32_e32 v22, 16, v8
	v_and_b32_e32 v8, 0xffff0000, v8
	v_lshlrev_b32_e32 v23, 16, v9
	v_and_b32_e32 v9, 0xffff0000, v9
	v_add_f32_e32 v6, v19, v6
	v_add_f32_e32 v7, v13, v7
	v_add_f32_e32 v18, v18, v20
	v_add_f32_e32 v12, v12, v21
	v_add_f32_e32 v8, v15, v8
	v_add_f32_e32 v9, v17, v9
	v_cvt_pk_bf16_f32 v6, v18, v6
	v_cvt_pk_bf16_f32 v7, v12, v7
	v_add_f32_e32 v13, v14, v22
	v_add_f32_e32 v14, v16, v23
	v_cvt_pk_bf16_f32 v8, v13, v8
	v_cvt_pk_bf16_f32 v9, v14, v9
	global_store_dwordx4 v[10:11], v[6:9], off
	v_lshlrev_b32_e32 v11, 16, v7
	v_lshlrev_b32_e32 v10, 16, v6
	v_and_b32_e32 v7, 0xffff0000, v7
	v_and_b32_e32 v6, 0xffff0000, v6
	v_and_b32_e32 v15, 0xffff0000, v8
	v_and_b32_e32 v14, 0xffff0000, v9
	v_pk_mul_f32 v[6:7], v[6:7], v[6:7]
	v_lshlrev_b32_e32 v12, 16, v9
	v_lshlrev_b32_e32 v13, 16, v8
	v_pk_mul_f32 v[8:9], v[14:15], v[14:15]
	v_pk_fma_f32 v[6:7], v[10:11], v[10:11], v[6:7]
	v_pk_fma_f32 v[8:9], v[12:13], v[12:13], v[8:9]
	v_add_f32_e32 v6, v6, v7
	v_add_f32_e32 v6, v9, v6
	v_add_f32_e32 v27, v8, v6
.LBB0_555:
	global_load_dwordx4 v[10:13], v[220:221], off offset:16
	global_load_dwordx4 v[14:17], v[220:221], off
	global_load_dwordx4 v[6:9], v[64:65], off offset:64
	s_cmp_lg_u32 s68, 4
	s_cbranch_scc1 .Lpmh_skip1
	v_lshl_add_u64 v[204:205], v[64:65], 0, s[52:53]
	global_load_dwordx4 v[192:195], v[204:205], off offset:64
	v_lshl_add_u64 v[204:205], v[64:65], 0, s[54:55]
	global_load_dwordx4 v[196:199], v[204:205], off offset:64
	v_lshl_add_u64 v[204:205], v[64:65], 0, s[56:57]
	global_load_dwordx4 v[200:203], v[204:205], off offset:64
.Lpmh_skip1:
	v_mov_b32_e32 v55, v54
	v_pk_mul_f32 v[22:23], v[162:163], v[54:55]
	v_mov_b32_e32 v18, v54
	v_mov_b32_e32 v19, v54
	v_pk_mul_f32 v[20:21], v[160:161], v[18:19]
	v_pk_mul_f32 v[24:25], v[154:155], v[54:55]
	v_pk_mul_f32 v[18:19], v[152:153], v[18:19]
	s_and_b64 vcc, exec, s[40:41]
	s_waitcnt vmcnt(2)
	v_pk_mul_f32 v[24:25], v[24:25], v[10:11]
	s_waitcnt vmcnt(1)
	v_pk_mul_f32 v[22:23], v[22:23], v[14:15]
	s_waitcnt vmcnt(0)
	v_lshlrev_b32_e32 v71, 16, v6
	v_and_b32_e32 v6, 0xffff0000, v6
	v_add_f32_e32 v22, v22, v71
	v_add_f32_e32 v6, v23, v6
	v_pk_mul_f32 v[20:21], v[20:21], v[16:17]
	v_cvt_pk_bf16_f32 v6, v22, v6
	v_lshlrev_b32_e32 v22, 16, v7
	v_and_b32_e32 v7, 0xffff0000, v7
	v_add_f32_e32 v20, v20, v22
	v_add_f32_e32 v7, v21, v7
	v_cvt_pk_bf16_f32 v7, v20, v7
	v_lshlrev_b32_e32 v20, 16, v8
	v_and_b32_e32 v8, 0xffff0000, v8
	v_add_f32_e32 v20, v24, v20
	v_add_f32_e32 v8, v25, v8
	v_pk_mul_f32 v[18:19], v[18:19], v[12:13]
	v_cvt_pk_bf16_f32 v8, v20, v8
	v_lshlrev_b32_e32 v20, 16, v9
	v_and_b32_e32 v9, 0xffff0000, v9
	v_add_f32_e32 v9, v19, v9
	v_add_f32_e32 v18, v18, v20
	v_cvt_pk_bf16_f32 v9, v18, v9
	global_store_dwordx4 v[68:69], v[6:9], off offset:64
	s_cbranch_vccz .LBB0_591
	s_and_b64 vcc, exec, s[40:41]
	s_cbranch_vccz .LBB0_592

.LBB0_558:
	v_lshlrev_b64 v[18:19], 10, v[88:89]
	v_lshl_add_u64 v[18:19], v[18:19], 0, v[212:213]
	v_lshlrev_b64 v[22:23], 1, v[18:19]
	v_lshl_add_u64 v[18:19], s[36:37], 0, v[22:23]
	v_mov_b64_e32 v[18:19], v[200:201]
	v_mov_b64_e32 v[20:21], v[202:203]
	v_pk_mul_f32 v[24:25], v[94:95], v[70:71] op_sel_hi:[1,0]
	v_pk_mul_f32 v[90:91], v[90:91], v[70:71] op_sel_hi:[1,0]
	v_pk_mul_f32 v[94:95], v[96:97], v[70:71] op_sel_hi:[1,0]
	v_pk_mul_f32 v[92:93], v[92:93], v[70:71] op_sel_hi:[1,0]
	v_pk_mul_f32 v[16:17], v[24:25], v[16:17]
	v_pk_mul_f32 v[12:13], v[90:91], v[12:13]
	v_pk_mul_f32 v[14:15], v[94:95], v[14:15]
	v_pk_mul_f32 v[10:11], v[92:93], v[10:11]
	v_lshl_add_u64 v[22:23], s[44:45], 0, v[22:23]
	v_lshlrev_b32_e32 v25, 16, v19
	v_and_b32_e32 v19, 0xffff0000, v19
	v_lshlrev_b32_e32 v90, 16, v21
	v_and_b32_e32 v21, 0xffff0000, v21
	v_lshlrev_b32_e32 v24, 16, v18
	v_and_b32_e32 v18, 0xffff0000, v18
	v_lshlrev_b32_e32 v71, 16, v20
	v_and_b32_e32 v20, 0xffff0000, v20
	v_add_f32_e32 v16, v16, v25
	v_add_f32_e32 v17, v17, v19
	v_add_f32_e32 v13, v13, v21
	v_add_f32_e32 v14, v14, v24
	v_add_f32_e32 v15, v15, v18
	v_add_f32_e32 v18, v10, v71
	v_add_f32_e32 v19, v11, v20
	v_add_f32_e32 v20, v12, v90
	v_cvt_pk_bf16_f32 v10, v14, v15
	v_cvt_pk_bf16_f32 v11, v16, v17
	v_cvt_pk_bf16_f32 v12, v18, v19
	v_cvt_pk_bf16_f32 v13, v20, v13
	global_store_dwordx4 v[22:23], v[10:13], off offset:64
	v_and_b32_e32 v17, 0xffff0000, v10
	v_and_b32_e32 v16, 0xffff0000, v11
	v_lshlrev_b32_e32 v14, 16, v11
	v_lshlrev_b32_e32 v15, 16, v10
	v_lshlrev_b32_e32 v10, 16, v13
	v_lshlrev_b32_e32 v11, 16, v12
	v_and_b32_e32 v19, 0xffff0000, v12
	v_and_b32_e32 v18, 0xffff0000, v13
	v_pk_mul_f32 v[12:13], v[16:17], v[16:17]
	v_pk_mul_f32 v[16:17], v[18:19], v[18:19]
	v_pk_fma_f32 v[12:13], v[14:15], v[14:15], v[12:13]
	v_pk_fma_f32 v[10:11], v[10:11], v[10:11], v[16:17]
	v_add_f32_e32 v13, v27, v13
	v_add_f32_e32 v12, v12, v13
	v_add_f32_e32 v11, v11, v12
	v_add_f32_e32 v27, v10, v11
.LBB0_559:
	global_load_dwordx4 v[14:17], v[222:223], off offset:16
	global_load_dwordx4 v[18:21], v[222:223], off
	global_load_dwordx4 v[10:13], v[64:65], off offset:128
	s_cmp_lg_u32 s68, 4
	s_cbranch_scc1 .Lpmh_skip2
	v_lshl_add_u64 v[204:205], v[64:65], 0, s[52:53]
	global_load_dwordx4 v[192:195], v[204:205], off offset:128
	v_lshl_add_u64 v[204:205], v[64:65], 0, s[54:55]
	global_load_dwordx4 v[196:199], v[204:205], off offset:128
	v_lshl_add_u64 v[204:205], v[64:65], 0, s[56:57]
	global_load_dwordx4 v[200:203], v[204:205], off offset:128
.Lpmh_skip2:
	v_pk_mul_f32 v[90:91], v[148:149], v[54:55]
	v_mov_b32_e32 v22, v54
	v_mov_b32_e32 v23, v54
	v_pk_mul_f32 v[24:25], v[150:151], v[22:23]
	v_pk_mul_f32 v[92:93], v[140:141], v[54:55]
	v_pk_mul_f32 v[22:23], v[142:143], v[22:23]
	s_and_b64 vcc, exec, s[40:41]
	s_waitcnt vmcnt(2)
	v_pk_mul_f32 v[92:93], v[92:93], v[14:15]
	s_waitcnt vmcnt(1)
	v_pk_mul_f32 v[90:91], v[90:91], v[18:19]
	s_waitcnt vmcnt(0)
	v_lshlrev_b32_e32 v71, 16, v10
	v_and_b32_e32 v10, 0xffff0000, v10
	v_add_f32_e32 v71, v90, v71
	v_add_f32_e32 v10, v91, v10
	v_pk_mul_f32 v[24:25], v[24:25], v[20:21]
	v_cvt_pk_bf16_f32 v10, v71, v10
	v_lshlrev_b32_e32 v71, 16, v11
	v_and_b32_e32 v11, 0xffff0000, v11
	v_add_f32_e32 v24, v24, v71
	v_add_f32_e32 v11, v25, v11
	v_cvt_pk_bf16_f32 v11, v24, v11
	v_lshlrev_b32_e32 v24, 16, v12
	v_and_b32_e32 v12, 0xffff0000, v12
	v_add_f32_e32 v24, v92, v24
	v_add_f32_e32 v12, v93, v12
	v_pk_mul_f32 v[22:23], v[22:23], v[16:17]
	v_cvt_pk_bf16_f32 v12, v24, v12
	v_lshlrev_b32_e32 v24, 16, v13
	v_and_b32_e32 v13, 0xffff0000, v13
	v_add_f32_e32 v13, v23, v13
	v_add_f32_e32 v22, v22, v24
	v_cvt_pk_bf16_f32 v13, v22, v13
	global_store_dwordx4 v[68:69], v[10:13], off offset:128
	s_cbranch_vccz .LBB0_593
	s_and_b64 vcc, exec, s[40:41]
	s_cbranch_vccz .LBB0_594

.LBB0_562:
	v_lshlrev_b64 v[22:23], 10, v[88:89]
	v_lshl_add_u64 v[22:23], v[22:23], 0, v[212:213]
	v_lshlrev_b64 v[56:57], 1, v[22:23]
	v_lshl_add_u64 v[22:23], s[36:37], 0, v[56:57]
	v_mov_b64_e32 v[22:23], v[200:201]
	v_mov_b64_e32 v[24:25], v[202:203]
	v_pk_mul_f32 v[50:51], v[50:51], v[70:71] op_sel_hi:[1,0]
	v_pk_mul_f32 v[38:39], v[38:39], v[70:71] op_sel_hi:[1,0]
	v_pk_mul_f32 v[48:49], v[48:49], v[70:71] op_sel_hi:[1,0]
	v_pk_mul_f32 v[52:53], v[52:53], v[70:71] op_sel_hi:[1,0]
	v_pk_mul_f32 v[20:21], v[50:51], v[20:21]
	v_pk_mul_f32 v[16:17], v[38:39], v[16:17]
	v_pk_mul_f32 v[14:15], v[48:49], v[14:15]
	v_pk_mul_f32 v[18:19], v[52:53], v[18:19]
	v_lshl_add_u64 v[38:39], s[44:45], 0, v[56:57]
	v_lshlrev_b32_e32 v49, 16, v23
	v_and_b32_e32 v23, 0xffff0000, v23
	v_lshlrev_b32_e32 v51, 16, v25
	v_and_b32_e32 v25, 0xffff0000, v25
	v_lshlrev_b32_e32 v48, 16, v22
	v_and_b32_e32 v22, 0xffff0000, v22
	v_lshlrev_b32_e32 v50, 16, v24
	v_and_b32_e32 v24, 0xffff0000, v24
	v_add_f32_e32 v20, v20, v49
	v_add_f32_e32 v21, v21, v23
	v_add_f32_e32 v17, v17, v25
	v_add_f32_e32 v18, v18, v48
	v_add_f32_e32 v19, v19, v22
	v_add_f32_e32 v22, v14, v50
	v_add_f32_e32 v23, v15, v24
	v_add_f32_e32 v24, v16, v51
	v_cvt_pk_bf16_f32 v14, v18, v19
	v_cvt_pk_bf16_f32 v15, v20, v21
	v_cvt_pk_bf16_f32 v16, v22, v23
	v_cvt_pk_bf16_f32 v17, v24, v17
	global_store_dwordx4 v[38:39], v[14:17], off offset:128
	v_and_b32_e32 v21, 0xffff0000, v14
	v_and_b32_e32 v20, 0xffff0000, v15
	v_lshlrev_b32_e32 v18, 16, v15
	v_lshlrev_b32_e32 v19, 16, v14
	v_lshlrev_b32_e32 v14, 16, v17
	v_lshlrev_b32_e32 v15, 16, v16
	v_and_b32_e32 v23, 0xffff0000, v16
	v_and_b32_e32 v22, 0xffff0000, v17
	v_pk_mul_f32 v[16:17], v[20:21], v[20:21]
	v_pk_mul_f32 v[20:21], v[22:23], v[22:23]
	v_pk_fma_f32 v[16:17], v[18:19], v[18:19], v[16:17]
	v_pk_fma_f32 v[14:15], v[14:15], v[14:15], v[20:21]
	v_add_f32_e32 v17, v27, v17
	v_add_f32_e32 v16, v16, v17
	v_add_f32_e32 v15, v15, v16
	v_add_f32_e32 v27, v14, v15
.LBB0_563:
	global_load_dwordx4 v[22:25], v[224:225], off
	global_load_dwordx4 v[18:21], v[224:225], off offset:16
	global_load_dwordx4 v[14:17], v[64:65], off offset:192
	s_cmp_lg_u32 s68, 4
	s_cbranch_scc1 .Lpmh_skip3
	v_lshl_add_u64 v[204:205], v[64:65], 0, s[52:53]
	global_load_dwordx4 v[192:195], v[204:205], off offset:192
	v_lshl_add_u64 v[204:205], v[64:65], 0, s[54:55]
	global_load_dwordx4 v[196:199], v[204:205], off offset:192
	v_lshl_add_u64 v[204:205], v[64:65], 0, s[56:57]
	global_load_dwordx4 v[200:203], v[204:205], off offset:192
.Lpmh_skip3:
	v_mov_b32_e32 v38, v54
	v_mov_b32_e32 v39, v54
	v_pk_mul_f32 v[48:49], v[138:139], v[54:55]
	v_pk_mul_f32 v[50:51], v[136:137], v[54:55]
	v_pk_mul_f32 v[52:53], v[132:133], v[38:39]
	v_pk_mul_f32 v[38:39], v[134:135], v[38:39]
	s_and_b64 vcc, exec, s[40:41]
	s_waitcnt vmcnt(2)
	v_pk_mul_f32 v[52:53], v[52:53], v[24:25]
	v_pk_mul_f32 v[48:49], v[48:49], v[22:23]
	s_waitcnt vmcnt(1)
	v_pk_mul_f32 v[38:39], v[38:39], v[20:21]
	v_pk_mul_f32 v[50:51], v[50:51], v[18:19]
	s_waitcnt vmcnt(0)
	v_lshlrev_b32_e32 v54, 16, v14
	v_and_b32_e32 v14, 0xffff0000, v14
	v_lshlrev_b32_e32 v55, 16, v15
	v_and_b32_e32 v15, 0xffff0000, v15
	v_lshlrev_b32_e32 v56, 16, v16
	v_and_b32_e32 v16, 0xffff0000, v16
	v_lshlrev_b32_e32 v57, 16, v17
	v_and_b32_e32 v17, 0xffff0000, v17
	v_add_f32_e32 v14, v49, v14
	v_add_f32_e32 v15, v53, v15
	v_add_f32_e32 v16, v51, v16
	v_add_f32_e32 v17, v39, v17
	v_add_f32_e32 v48, v48, v54
	v_add_f32_e32 v49, v52, v55
	v_add_f32_e32 v50, v50, v56
	v_add_f32_e32 v38, v38, v57
	v_cvt_pk_bf16_f32 v14, v48, v14
	v_cvt_pk_bf16_f32 v15, v49, v15
	v_cvt_pk_bf16_f32 v16, v50, v16
	v_cvt_pk_bf16_f32 v17, v38, v17
	global_store_dwordx4 v[68:69], v[14:17], off offset:192
	s_cbranch_vccz .LBB0_595
	s_and_b64 vcc, exec, s[40:41]
	s_cbranch_vccz .LBB0_596

.LBB0_566:
	v_lshlrev_b64 v[28:29], 10, v[88:89]
	v_lshl_add_u64 v[28:29], v[28:29], 0, v[212:213]
	v_lshlrev_b64 v[28:29], 1, v[28:29]
	v_lshl_add_u64 v[38:39], s[36:37], 0, v[28:29]
	v_mov_b64_e32 v[38:39], v[200:201]
	v_mov_b64_e32 v[40:41], v[202:203]
	v_pk_mul_f32 v[34:35], v[34:35], v[70:71] op_sel_hi:[1,0]
	v_pk_mul_f32 v[36:37], v[36:37], v[70:71] op_sel_hi:[1,0]
	v_pk_mul_f32 v[30:31], v[30:31], v[70:71] op_sel_hi:[1,0]
	v_pk_mul_f32 v[32:33], v[32:33], v[70:71] op_sel_hi:[1,0]
	v_pk_mul_f32 v[24:25], v[34:35], v[24:25]
	v_pk_mul_f32 v[22:23], v[36:37], v[22:23]
	v_pk_mul_f32 v[20:21], v[30:31], v[20:21]
	v_pk_mul_f32 v[18:19], v[32:33], v[18:19]
	v_lshl_add_u64 v[28:29], s[44:45], 0, v[28:29]
	v_lshlrev_b32_e32 v0, 16, v38
	v_and_b32_e32 v26, 0xffff0000, v38
	v_lshlrev_b32_e32 v30, 16, v39
	v_and_b32_e32 v31, 0xffff0000, v39
	v_lshlrev_b32_e32 v32, 16, v40
	v_and_b32_e32 v35, 0xffff0000, v41
	v_and_b32_e32 v33, 0xffff0000, v40
	v_lshlrev_b32_e32 v34, 16, v41
	v_add_f32_e32 v0, v22, v0
	v_add_f32_e32 v22, v23, v26
	v_add_f32_e32 v23, v24, v30
	v_add_f32_e32 v24, v25, v31
	v_add_f32_e32 v25, v18, v32
	v_add_f32_e32 v21, v21, v35
	v_add_f32_e32 v26, v19, v33
	v_add_f32_e32 v30, v20, v34
	v_cvt_pk_bf16_f32 v18, v0, v22
	v_cvt_pk_bf16_f32 v19, v23, v24
	v_cvt_pk_bf16_f32 v20, v25, v26
	v_cvt_pk_bf16_f32 v21, v30, v21
	global_store_dwordx4 v[28:29], v[18:21], off offset:192
	v_and_b32_e32 v25, 0xffff0000, v18
	v_and_b32_e32 v24, 0xffff0000, v19
	v_lshlrev_b32_e32 v22, 16, v19
	v_lshlrev_b32_e32 v23, 16, v18
	v_lshlrev_b32_e32 v18, 16, v21
	v_lshlrev_b32_e32 v19, 16, v20
	v_and_b32_e32 v29, 0xffff0000, v20
	v_and_b32_e32 v28, 0xffff0000, v21
	v_pk_mul_f32 v[20:21], v[24:25], v[24:25]
	v_pk_mul_f32 v[24:25], v[28:29], v[28:29]
	v_pk_fma_f32 v[20:21], v[22:23], v[22:23], v[20:21]
	v_pk_fma_f32 v[18:19], v[18:19], v[18:19], v[24:25]
	v_add_f32_e32 v0, v27, v21
	v_add_f32_e32 v0, v20, v0
	v_add_f32_e32 v0, v19, v0
	v_add_f32_e32 v27, v18, v0

.LBB0_591:
	v_lshlrev_b64 v[18:19], 10, v[66:67]
	v_lshl_add_u64 v[18:19], v[18:19], 0, v[212:213]
	v_lshlrev_b64 v[22:23], 1, v[18:19]
	v_lshl_add_u64 v[18:19], s[36:37], 0, v[22:23]
	v_mov_b64_e32 v[18:19], v[192:193]
	v_mov_b64_e32 v[20:21], v[194:195]
	v_pk_mul_f32 v[100:101], v[168:169], v[0:1] op_sel_hi:[1,0]
	v_pk_mul_f32 v[24:25], v[166:167], v[0:1] op_sel_hi:[1,0]
	v_pk_mul_f32 v[100:101], v[100:101], v[14:15]
	v_pk_mul_f32 v[24:25], v[24:25], v[16:17]
	v_pk_mul_f32 v[108:109], v[164:165], v[0:1] op_sel_hi:[1,0]
	v_pk_mul_f32 v[102:103], v[158:159], v[0:1] op_sel_hi:[1,0]
	v_pk_mul_f32 v[108:109], v[108:109], v[10:11]
	v_pk_mul_f32 v[102:103], v[102:103], v[12:13]
	v_lshl_add_u64 v[22:23], s[44:45], 0, v[22:23]
	v_lshlrev_b32_e32 v71, 16, v18
	v_and_b32_e32 v18, 0xffff0000, v18
	v_add_f32_e32 v71, v100, v71
	v_add_f32_e32 v18, v101, v18
	v_cvt_pk_bf16_f32 v18, v71, v18
	v_lshlrev_b32_e32 v71, 16, v19
	v_and_b32_e32 v19, 0xffff0000, v19
	v_add_f32_e32 v24, v24, v71
	v_add_f32_e32 v19, v25, v19
	v_cvt_pk_bf16_f32 v19, v24, v19
	v_lshlrev_b32_e32 v24, 16, v20
	v_and_b32_e32 v20, 0xffff0000, v20
	v_add_f32_e32 v24, v108, v24
	v_add_f32_e32 v20, v109, v20
	v_cvt_pk_bf16_f32 v20, v24, v20
	v_lshlrev_b32_e32 v24, 16, v21
	v_and_b32_e32 v21, 0xffff0000, v21
	v_add_f32_e32 v24, v102, v24
	v_add_f32_e32 v21, v103, v21
	v_cvt_pk_bf16_f32 v21, v24, v21
	v_and_b32_e32 v25, 0xffff0000, v18
	v_and_b32_e32 v24, 0xffff0000, v19
	global_store_dwordx4 v[22:23], v[18:21], off offset:64
	v_lshlrev_b32_e32 v22, 16, v19
	v_lshlrev_b32_e32 v23, 16, v18
	v_pk_mul_f32 v[18:19], v[24:25], v[24:25]
	s_nop 0
	v_pk_fma_f32 v[18:19], v[22:23], v[22:23], v[18:19]
	v_and_b32_e32 v23, 0xffff0000, v20
	v_add_f32_e32 v19, v105, v19
	v_and_b32_e32 v22, 0xffff0000, v21
	v_add_f32_e32 v24, v18, v19
	v_lshlrev_b32_e32 v18, 16, v21
	v_lshlrev_b32_e32 v19, 16, v20
	v_pk_mul_f32 v[20:21], v[22:23], v[22:23]
	s_nop 0
	v_pk_fma_f32 v[18:19], v[18:19], v[18:19], v[20:21]
	s_nop 0
	v_add_f32_e32 v19, v19, v24
	v_add_f32_e32 v105, v18, v19
	s_and_b64 vcc, exec, s[40:41]
	s_cbranch_vccnz .LBB0_557
.LBB0_592:
	v_lshlrev_b64 v[18:19], 10, v[28:29]
	v_lshl_add_u64 v[18:19], v[18:19], 0, v[212:213]
	v_lshlrev_b64 v[22:23], 1, v[18:19]
	v_lshl_add_u64 v[18:19], s[36:37], 0, v[22:23]
	v_mov_b64_e32 v[18:19], v[196:197]
	v_mov_b64_e32 v[20:21], v[198:199]
	v_pk_mul_f32 v[100:101], v[156:157], v[26:27] op_sel_hi:[1,0]
	v_pk_mul_f32 v[24:25], v[146:147], v[26:27] op_sel_hi:[1,0]
	v_pk_mul_f32 v[100:101], v[100:101], v[14:15]
	v_pk_mul_f32 v[24:25], v[24:25], v[16:17]
	v_pk_mul_f32 v[102:103], v[144:145], v[26:27] op_sel_hi:[1,0]
	v_pk_mul_f32 v[98:99], v[98:99], v[26:27] op_sel_hi:[1,0]
	v_pk_mul_f32 v[102:103], v[102:103], v[10:11]
	v_pk_mul_f32 v[98:99], v[98:99], v[12:13]
	v_lshl_add_u64 v[22:23], s[44:45], 0, v[22:23]
	v_lshlrev_b32_e32 v71, 16, v18
	v_and_b32_e32 v18, 0xffff0000, v18
	v_add_f32_e32 v71, v100, v71
	v_add_f32_e32 v18, v101, v18
	v_cvt_pk_bf16_f32 v18, v71, v18
	v_lshlrev_b32_e32 v71, 16, v19
	v_and_b32_e32 v19, 0xffff0000, v19
	v_add_f32_e32 v24, v24, v71
	v_add_f32_e32 v19, v25, v19
	v_cvt_pk_bf16_f32 v19, v24, v19
	v_lshlrev_b32_e32 v24, 16, v20
	v_and_b32_e32 v20, 0xffff0000, v20
	v_add_f32_e32 v24, v102, v24
	v_add_f32_e32 v20, v103, v20
	v_cvt_pk_bf16_f32 v20, v24, v20
	v_lshlrev_b32_e32 v24, 16, v21
	v_and_b32_e32 v21, 0xffff0000, v21
	v_add_f32_e32 v24, v98, v24
	v_add_f32_e32 v21, v99, v21
	v_cvt_pk_bf16_f32 v21, v24, v21
	v_and_b32_e32 v25, 0xffff0000, v18
	v_and_b32_e32 v24, 0xffff0000, v19
	global_store_dwordx4 v[22:23], v[18:21], off offset:64
	v_lshlrev_b32_e32 v22, 16, v19
	v_lshlrev_b32_e32 v23, 16, v18
	v_pk_mul_f32 v[18:19], v[24:25], v[24:25]
	s_nop 0
	v_pk_fma_f32 v[18:19], v[22:23], v[22:23], v[18:19]
	v_and_b32_e32 v23, 0xffff0000, v20
	v_add_f32_e32 v19, v106, v19
	v_and_b32_e32 v22, 0xffff0000, v21
	v_add_f32_e32 v24, v18, v19
	v_lshlrev_b32_e32 v18, 16, v21
	v_lshlrev_b32_e32 v19, 16, v20
	v_pk_mul_f32 v[20:21], v[22:23], v[22:23]
	s_nop 0
	v_pk_fma_f32 v[18:19], v[18:19], v[18:19], v[20:21]
	s_nop 0
	v_add_f32_e32 v19, v19, v24
	v_add_f32_e32 v106, v18, v19
	s_and_b64 vcc, exec, s[40:41]
	s_cbranch_vccz .LBB0_558
	s_branch .LBB0_559
.LBB0_593:
	v_lshlrev_b64 v[22:23], 10, v[66:67]
	v_lshl_add_u64 v[22:23], v[22:23], 0, v[212:213]
	v_lshlrev_b64 v[90:91], 1, v[22:23]
	v_lshl_add_u64 v[22:23], s[36:37], 0, v[90:91]
	v_mov_b64_e32 v[22:23], v[192:193]
	v_mov_b64_e32 v[24:25], v[194:195]
	v_pk_mul_f32 v[86:87], v[86:87], v[0:1] op_sel_hi:[1,0]
	v_pk_mul_f32 v[84:85], v[84:85], v[0:1] op_sel_hi:[1,0]
	v_pk_mul_f32 v[86:87], v[86:87], v[18:19]
	v_pk_mul_f32 v[84:85], v[84:85], v[20:21]
	v_pk_mul_f32 v[82:83], v[82:83], v[0:1] op_sel_hi:[1,0]
	v_pk_mul_f32 v[80:81], v[80:81], v[0:1] op_sel_hi:[1,0]
	v_pk_mul_f32 v[82:83], v[82:83], v[14:15]
	v_pk_mul_f32 v[80:81], v[80:81], v[16:17]
	v_lshlrev_b32_e32 v71, 16, v22
	v_and_b32_e32 v22, 0xffff0000, v22
	v_add_f32_e32 v71, v86, v71
	v_add_f32_e32 v22, v87, v22
	v_cvt_pk_bf16_f32 v22, v71, v22
	v_lshlrev_b32_e32 v71, 16, v23
	v_and_b32_e32 v23, 0xffff0000, v23
	v_add_f32_e32 v71, v84, v71
	v_add_f32_e32 v23, v85, v23
	v_cvt_pk_bf16_f32 v23, v71, v23
	v_lshlrev_b32_e32 v71, 16, v24
	v_and_b32_e32 v24, 0xffff0000, v24
	v_add_f32_e32 v71, v82, v71
	v_add_f32_e32 v24, v83, v24
	v_cvt_pk_bf16_f32 v24, v71, v24
	v_lshlrev_b32_e32 v71, 16, v25
	v_and_b32_e32 v25, 0xffff0000, v25
	v_add_f32_e32 v71, v80, v71
	v_add_f32_e32 v25, v81, v25
	v_lshl_add_u64 v[80:81], s[44:45], 0, v[90:91]
	v_and_b32_e32 v83, 0xffff0000, v22
	v_and_b32_e32 v82, 0xffff0000, v23
	v_cvt_pk_bf16_f32 v25, v71, v25
	global_store_dwordx4 v[80:81], v[22:25], off offset:128
	v_lshlrev_b32_e32 v80, 16, v23
	v_lshlrev_b32_e32 v81, 16, v22
	v_pk_mul_f32 v[22:23], v[82:83], v[82:83]
	s_nop 0
	v_pk_fma_f32 v[22:23], v[80:81], v[80:81], v[22:23]
	v_and_b32_e32 v81, 0xffff0000, v24
	v_add_f32_e32 v23, v105, v23
	v_and_b32_e32 v80, 0xffff0000, v25
	v_add_f32_e32 v71, v22, v23
	v_lshlrev_b32_e32 v22, 16, v25
	v_lshlrev_b32_e32 v23, 16, v24
	v_pk_mul_f32 v[24:25], v[80:81], v[80:81]
	s_nop 0
	v_pk_fma_f32 v[22:23], v[22:23], v[22:23], v[24:25]
	s_nop 0
	v_add_f32_e32 v23, v23, v71
	v_add_f32_e32 v105, v22, v23
	s_and_b64 vcc, exec, s[40:41]
	s_cbranch_vccnz .LBB0_561
.LBB0_594:
	v_lshlrev_b64 v[22:23], 10, v[28:29]
	v_lshl_add_u64 v[22:23], v[22:23], 0, v[212:213]
	v_lshlrev_b64 v[80:81], 1, v[22:23]
	v_lshl_add_u64 v[22:23], s[36:37], 0, v[80:81]
	v_mov_b64_e32 v[22:23], v[196:197]
	v_mov_b64_e32 v[24:25], v[198:199]
	v_pk_mul_f32 v[62:63], v[62:63], v[26:27] op_sel_hi:[1,0]
	v_pk_mul_f32 v[60:61], v[60:61], v[26:27] op_sel_hi:[1,0]
	v_pk_mul_f32 v[62:63], v[62:63], v[18:19]
	v_pk_mul_f32 v[60:61], v[60:61], v[20:21]
	v_pk_mul_f32 v[58:59], v[58:59], v[26:27] op_sel_hi:[1,0]
	v_pk_mul_f32 v[56:57], v[56:57], v[26:27] op_sel_hi:[1,0]
	v_pk_mul_f32 v[58:59], v[58:59], v[14:15]
	v_pk_mul_f32 v[56:57], v[56:57], v[16:17]
	v_lshlrev_b32_e32 v71, 16, v22
	v_and_b32_e32 v22, 0xffff0000, v22
	v_add_f32_e32 v62, v62, v71
	v_add_f32_e32 v22, v63, v22
	v_cvt_pk_bf16_f32 v22, v62, v22
	v_lshlrev_b32_e32 v62, 16, v23
	v_and_b32_e32 v23, 0xffff0000, v23
	v_add_f32_e32 v60, v60, v62
	v_add_f32_e32 v23, v61, v23
	v_cvt_pk_bf16_f32 v23, v60, v23
	v_lshlrev_b32_e32 v60, 16, v24
	v_and_b32_e32 v24, 0xffff0000, v24
	v_add_f32_e32 v58, v58, v60
	v_add_f32_e32 v24, v59, v24
	v_cvt_pk_bf16_f32 v24, v58, v24
	v_lshlrev_b32_e32 v58, 16, v25
	v_and_b32_e32 v25, 0xffff0000, v25
	v_add_f32_e32 v56, v56, v58
	v_add_f32_e32 v25, v57, v25
	v_cvt_pk_bf16_f32 v25, v56, v25
	v_lshl_add_u64 v[56:57], s[44:45], 0, v[80:81]
	v_and_b32_e32 v59, 0xffff0000, v22
	v_and_b32_e32 v58, 0xffff0000, v23
	global_store_dwordx4 v[56:57], v[22:25], off offset:128
	v_lshlrev_b32_e32 v56, 16, v23
	v_lshlrev_b32_e32 v57, 16, v22
	v_pk_mul_f32 v[22:23], v[58:59], v[58:59]
	s_nop 0
	v_pk_fma_f32 v[22:23], v[56:57], v[56:57], v[22:23]
	v_and_b32_e32 v57, 0xffff0000, v24
	v_add_f32_e32 v23, v106, v23
	v_and_b32_e32 v56, 0xffff0000, v25
	v_add_f32_e32 v58, v22, v23
	v_lshlrev_b32_e32 v22, 16, v25
	v_lshlrev_b32_e32 v23, 16, v24
	v_pk_mul_f32 v[24:25], v[56:57], v[56:57]
	s_nop 0
	v_pk_fma_f32 v[22:23], v[22:23], v[22:23], v[24:25]
	s_nop 0
	v_add_f32_e32 v23, v23, v58
	v_add_f32_e32 v106, v22, v23
	s_and_b64 vcc, exec, s[40:41]
	s_cbranch_vccz .LBB0_562
	s_branch .LBB0_563
.LBB0_595:
	v_lshlrev_b64 v[38:39], 10, v[66:67]
	v_lshl_add_u64 v[38:39], v[38:39], 0, v[212:213]
	v_lshlrev_b64 v[38:39], 1, v[38:39]
	v_lshl_add_u64 v[48:49], s[36:37], 0, v[38:39]
	v_mov_b64_e32 v[48:49], v[192:193]
	v_mov_b64_e32 v[50:51], v[194:195]
	v_pk_mul_f32 v[54:55], v[78:79], v[0:1] op_sel_hi:[1,0]
	v_pk_mul_f32 v[52:53], v[76:77], v[0:1] op_sel_hi:[1,0]
	v_pk_mul_f32 v[54:55], v[54:55], v[22:23]
	v_pk_mul_f32 v[56:57], v[72:73], v[0:1] op_sel_hi:[1,0]
	v_pk_mul_f32 v[58:59], v[74:75], v[0:1] op_sel_hi:[1,0]
	v_pk_mul_f32 v[52:53], v[52:53], v[24:25]
	v_pk_mul_f32 v[58:59], v[58:59], v[18:19]
	v_pk_mul_f32 v[56:57], v[56:57], v[20:21]
	v_lshl_add_u64 v[38:39], s[44:45], 0, v[38:39]
	v_lshlrev_b32_e32 v0, 16, v48
	v_and_b32_e32 v48, 0xffff0000, v48
	v_add_f32_e32 v0, v54, v0
	v_add_f32_e32 v48, v55, v48
	v_cvt_pk_bf16_f32 v48, v0, v48
	v_lshlrev_b32_e32 v0, 16, v49
	v_and_b32_e32 v49, 0xffff0000, v49
	v_add_f32_e32 v0, v52, v0
	v_add_f32_e32 v49, v53, v49
	v_cvt_pk_bf16_f32 v49, v0, v49
	v_lshlrev_b32_e32 v0, 16, v50
	v_and_b32_e32 v50, 0xffff0000, v50
	v_add_f32_e32 v0, v58, v0
	v_add_f32_e32 v50, v59, v50
	v_cvt_pk_bf16_f32 v50, v0, v50
	v_lshlrev_b32_e32 v0, 16, v51
	v_and_b32_e32 v51, 0xffff0000, v51
	v_add_f32_e32 v51, v57, v51
	v_and_b32_e32 v53, 0xffff0000, v48
	v_and_b32_e32 v52, 0xffff0000, v49
	v_add_f32_e32 v0, v56, v0
	v_cvt_pk_bf16_f32 v51, v0, v51
	global_store_dwordx4 v[38:39], v[48:51], off offset:192
	v_lshlrev_b32_e32 v38, 16, v49
	v_lshlrev_b32_e32 v39, 16, v48
	v_pk_mul_f32 v[48:49], v[52:53], v[52:53]
	s_nop 0
	v_pk_fma_f32 v[38:39], v[38:39], v[38:39], v[48:49]
	v_and_b32_e32 v49, 0xffff0000, v50
	v_add_f32_e32 v0, v105, v39
	v_and_b32_e32 v48, 0xffff0000, v51
	v_add_f32_e32 v0, v38, v0
	v_lshlrev_b32_e32 v38, 16, v51
	v_lshlrev_b32_e32 v39, 16, v50
	v_pk_mul_f32 v[48:49], v[48:49], v[48:49]
	s_nop 0
	v_pk_fma_f32 v[38:39], v[38:39], v[38:39], v[48:49]
	s_nop 0
	v_add_f32_e32 v0, v39, v0
	v_add_f32_e32 v105, v38, v0
	s_and_b64 vcc, exec, s[40:41]
	s_cbranch_vccnz .LBB0_565
.LBB0_596:
	v_lshlrev_b64 v[28:29], 10, v[28:29]
	v_lshl_add_u64 v[28:29], v[28:29], 0, v[212:213]
	v_lshlrev_b64 v[28:29], 1, v[28:29]
	v_lshl_add_u64 v[38:39], s[36:37], 0, v[28:29]
	v_mov_b64_e32 v[48:49], v[196:197]
	v_mov_b64_e32 v[50:51], v[198:199]
	v_pk_mul_f32 v[38:39], v[46:47], v[26:27] op_sel_hi:[1,0]
	v_pk_mul_f32 v[44:45], v[44:45], v[26:27] op_sel_hi:[1,0]
	v_pk_mul_f32 v[46:47], v[38:39], v[24:25]
	v_pk_mul_f32 v[38:39], v[44:45], v[22:23]
	v_pk_mul_f32 v[42:43], v[42:43], v[26:27] op_sel_hi:[1,0]
	v_pk_mul_f32 v[40:41], v[40:41], v[26:27] op_sel_hi:[1,0]
	v_pk_mul_f32 v[42:43], v[42:43], v[20:21]
	v_pk_mul_f32 v[40:41], v[40:41], v[18:19]
	v_lshl_add_u64 v[28:29], s[44:45], 0, v[28:29]
	v_lshlrev_b32_e32 v0, 16, v48
	v_and_b32_e32 v26, 0xffff0000, v48
	v_add_f32_e32 v0, v38, v0
	v_add_f32_e32 v26, v39, v26
	v_cvt_pk_bf16_f32 v38, v0, v26
	v_lshlrev_b32_e32 v0, 16, v49
	v_and_b32_e32 v26, 0xffff0000, v49
	v_add_f32_e32 v0, v46, v0
	v_add_f32_e32 v26, v47, v26
	v_cvt_pk_bf16_f32 v39, v0, v26
	v_lshlrev_b32_e32 v0, 16, v50
	v_and_b32_e32 v26, 0xffff0000, v50
	v_add_f32_e32 v0, v40, v0
	v_add_f32_e32 v26, v41, v26
	v_cvt_pk_bf16_f32 v40, v0, v26
	v_lshlrev_b32_e32 v0, 16, v51
	v_and_b32_e32 v26, 0xffff0000, v51
	v_add_f32_e32 v0, v42, v0
	v_add_f32_e32 v26, v43, v26
	v_and_b32_e32 v43, 0xffff0000, v38
	v_and_b32_e32 v42, 0xffff0000, v39
	v_cvt_pk_bf16_f32 v41, v0, v26
	global_store_dwordx4 v[28:29], v[38:41], off offset:192
	v_lshlrev_b32_e32 v28, 16, v39
	v_lshlrev_b32_e32 v29, 16, v38
	v_pk_mul_f32 v[38:39], v[42:43], v[42:43]
	s_nop 0
	v_pk_fma_f32 v[28:29], v[28:29], v[28:29], v[38:39]
	v_and_b32_e32 v39, 0xffff0000, v40
	v_add_f32_e32 v0, v106, v29
	v_and_b32_e32 v38, 0xffff0000, v41
	v_add_f32_e32 v0, v28, v0
	v_lshlrev_b32_e32 v28, 16, v41
	v_lshlrev_b32_e32 v29, 16, v40
	v_pk_mul_f32 v[38:39], v[38:39], v[38:39]
	s_nop 0
	v_pk_fma_f32 v[28:29], v[28:29], v[28:29], v[38:39]
	s_nop 0
	v_add_f32_e32 v0, v29, v0
	v_add_f32_e32 v106, v28, v0
	s_and_b64 vcc, exec, s[40:41]
	s_cbranch_vccz .LBB0_566
	s_branch .LBB0_567
